# K-loop shifted by 4 bytes so 6 of 8 MFMA half-runs start 8-byte aligned (code placement)
# speedup vs baseline: 1.0076x; 1.0076x over previous
.LBB0_246:
	s_andn2_b64 vcc, exec, s[18:19]
	s_cbranch_vccnz .Lk_zero_skip
	s_add_u32 s44, s44, 0x80
	s_addc_u32 s45, s45, 0
	s_add_u32 s23, s46, 0x100
	s_addc_u32 s48, s47, 0
	s_mov_b32 s46, 0
	s_add_i32 s49, s46, 2
	s_add_u32 s69, s44, 0x80
	s_addc_u32 s47, s45, 0
	s_add_i32 s80, 0, 0x10000
	s_cmp_eq_u32 s90, s46
	s_cselect_b32 s47, s65, s47
	s_cselect_b32 s46, s64, s69
	s_cselect_b32 s71, s67, s48
	s_cselect_b32 s70, s66, s23
	s_add_i32 s69, 0, 0x14000
	v_add_u32_e32 v140, s80, v227
	v_add_u32_e32 v152, s69, v227
	ds_read_b128 v[128:131], v140
	ds_read_b128 v[132:135], v140 offset:1024
	ds_read_b128 v[136:139], v140 offset:2048
	ds_read_b128 v[140:143], v140 offset:3072
	ds_read_b128 v[144:147], v152
	ds_read_b128 v[148:151], v152 offset:1024
	ds_read_b128 v[174:177], v152 offset:2048
	ds_read_b128 v[178:181], v152 offset:3072
	v_lshl_add_u64 v[210:211], s[44:45], 0, v[170:171]
	s_add_i32 m0, s50, 0xc000
	ds_read_b128 v[182:185], v230
	ds_read_b128 v[186:189], v230 offset:1024
	ds_read_b128 v[190:193], v230 offset:2048
	ds_read_b128 v[194:197], v230 offset:3072
	ds_read_b128 v[198:201], v230 offset:4096
	ds_read_b128 v[202:205], v230 offset:5120
	ds_read_b128 v[206:209], v230 offset:6144
	ds_read_b128 v[232:235], v230 offset:7168
	global_load_lds_dwordx4 v[210:211], off
	v_lshl_add_u64 v[210:211], s[44:45], 0, v[172:173]
	s_add_i32 m0, s50, 0xe000
	s_nop 0
	global_load_lds_dwordx4 v[210:211], off
	s_waitcnt vmcnt(8)
	s_waitcnt lgkmcnt(0)
	s_barrier
	s_setprio 1
	s_waitcnt lgkmcnt(0)
	v_mfma_f32_16x16x32_bf16 v[16:19], v[128:131], v[182:185], 0
	v_mfma_f32_16x16x32_bf16 v[28:31], v[136:139], v[182:185], 0
	v_mfma_f32_16x16x32_bf16 v[12:15], v[128:131], v[190:193], 0
	v_mfma_f32_16x16x32_bf16 v[8:11], v[136:139], v[190:193], 0
	v_mfma_f32_16x16x32_bf16 v[124:127], v[128:131], v[198:201], 0
	v_mfma_f32_16x16x32_bf16 v[120:123], v[136:139], v[198:201], 0
	v_mfma_f32_16x16x32_bf16 v[108:111], v[128:131], v[206:209], 0
	v_mfma_f32_16x16x32_bf16 v[104:107], v[136:139], v[206:209], 0
	v_mfma_f32_16x16x32_bf16 v[16:19], v[132:135], v[186:189], v[16:19]
	v_mfma_f32_16x16x32_bf16 v[28:31], v[140:143], v[186:189], v[28:31]
	v_mfma_f32_16x16x32_bf16 v[12:15], v[132:135], v[194:197], v[12:15]
	v_mfma_f32_16x16x32_bf16 v[8:11], v[140:143], v[194:197], v[8:11]
	v_mfma_f32_16x16x32_bf16 v[124:127], v[132:135], v[202:205], v[124:127]
	v_mfma_f32_16x16x32_bf16 v[120:123], v[140:143], v[202:205], v[120:123]
	v_mfma_f32_16x16x32_bf16 v[108:111], v[132:135], v[232:235], v[108:111]
	v_mfma_f32_16x16x32_bf16 v[104:107], v[140:143], v[232:235], v[104:107]
	s_setprio 0
	s_setprio 1
	v_mfma_f32_16x16x32_bf16 v[24:27], v[144:147], v[182:185], 0
	v_mfma_f32_16x16x32_bf16 v[20:23], v[174:177], v[182:185], 0
	v_mfma_f32_16x16x32_bf16 v[4:7], v[144:147], v[190:193], 0
	v_mfma_f32_16x16x32_bf16 v[0:3], v[174:177], v[190:193], 0
	v_mfma_f32_16x16x32_bf16 v[116:119], v[144:147], v[198:201], 0
	v_mfma_f32_16x16x32_bf16 v[112:115], v[174:177], v[198:201], 0
	v_mfma_f32_16x16x32_bf16 v[100:103], v[144:147], v[206:209], 0
	v_mfma_f32_16x16x32_bf16 v[96:99], v[174:177], v[206:209], 0
	v_mfma_f32_16x16x32_bf16 v[24:27], v[148:151], v[186:189], v[24:27]
	v_mfma_f32_16x16x32_bf16 v[20:23], v[178:181], v[186:189], v[20:23]
	v_mfma_f32_16x16x32_bf16 v[4:7], v[148:151], v[194:197], v[4:7]
	v_mfma_f32_16x16x32_bf16 v[0:3], v[178:181], v[194:197], v[0:3]
	v_mfma_f32_16x16x32_bf16 v[116:119], v[148:151], v[202:205], v[116:119]
	v_mfma_f32_16x16x32_bf16 v[112:115], v[178:181], v[202:205], v[112:115]
	v_mfma_f32_16x16x32_bf16 v[100:103], v[148:151], v[232:235], v[100:103]
	v_mfma_f32_16x16x32_bf16 v[96:99], v[178:181], v[232:235], v[96:99]
	s_setprio 0
	s_barrier
	s_add_i32 s80, s80, s3
	v_lshl_add_u64 v[210:211], s[70:71], 0, v[160:161]
	s_mov_b32 m0, s80
	ds_read_b128 v[182:185], v230 offset:16384
	ds_read_b128 v[186:189], v230 offset:17408
	ds_read_b128 v[190:193], v230 offset:18432
	ds_read_b128 v[194:197], v230 offset:19456
	ds_read_b128 v[198:201], v230 offset:20480
	ds_read_b128 v[202:205], v230 offset:21504
	ds_read_b128 v[206:209], v230 offset:22528
	ds_read_b128 v[232:235], v230 offset:23552
	global_load_lds_dwordx4 v[210:211], off
	s_add_i32 m0, s80, 0x2000
	v_lshl_add_u64 v[236:237], s[70:71], 0, v[164:165]
	s_add_u32 s70, s70, s26
	s_addc_u32 s71, s71, 0
	s_add_i32 s69, s69, s3
	global_load_lds_dwordx4 v[236:237], off
	v_lshl_add_u64 v[238:239], s[70:71], 0, v[160:161]
	s_mov_b32 m0, s69
	v_lshl_add_u64 v[240:241], s[70:71], 0, v[164:165]
	global_load_lds_dwordx4 v[238:239], off
	s_add_i32 m0, s69, 0x2000
	v_lshl_add_u64 v[242:243], s[46:47], 0, v[158:159]
	global_load_lds_dwordx4 v[240:241], off
	s_mov_b32 m0, s50
	v_lshl_add_u64 v[244:245], s[46:47], 0, v[162:163]
	global_load_lds_dwordx4 v[242:243], off
	s_mov_b32 m0, s51
	s_nop 0
	global_load_lds_dwordx4 v[244:245], off
	s_waitcnt vmcnt(8)
	s_waitcnt lgkmcnt(0)
	s_barrier
	s_setprio 1
	s_waitcnt lgkmcnt(0)
	v_mfma_f32_16x16x32_bf16 v[92:95], v[128:131], v[182:185], 0
	v_mfma_f32_16x16x32_bf16 v[88:91], v[136:139], v[182:185], 0
	v_mfma_f32_16x16x32_bf16 v[76:79], v[128:131], v[190:193], 0
	v_mfma_f32_16x16x32_bf16 v[72:75], v[136:139], v[190:193], 0
	v_mfma_f32_16x16x32_bf16 v[60:63], v[128:131], v[198:201], 0
	v_mfma_f32_16x16x32_bf16 v[56:59], v[136:139], v[198:201], 0
	v_mfma_f32_16x16x32_bf16 v[44:47], v[128:131], v[206:209], 0
	v_mfma_f32_16x16x32_bf16 v[40:43], v[136:139], v[206:209], 0
	v_mfma_f32_16x16x32_bf16 v[92:95], v[132:135], v[186:189], v[92:95]
	v_mfma_f32_16x16x32_bf16 v[88:91], v[140:143], v[186:189], v[88:91]
	v_mfma_f32_16x16x32_bf16 v[76:79], v[132:135], v[194:197], v[76:79]
	v_mfma_f32_16x16x32_bf16 v[72:75], v[140:143], v[194:197], v[72:75]
	v_mfma_f32_16x16x32_bf16 v[60:63], v[132:135], v[202:205], v[60:63]
	v_mfma_f32_16x16x32_bf16 v[56:59], v[140:143], v[202:205], v[56:59]
	v_mfma_f32_16x16x32_bf16 v[44:47], v[132:135], v[232:235], v[44:47]
	v_mfma_f32_16x16x32_bf16 v[40:43], v[140:143], v[232:235], v[40:43]
	s_setprio 0
	s_setprio 1
	v_mfma_f32_16x16x32_bf16 v[84:87], v[144:147], v[182:185], 0
	v_mfma_f32_16x16x32_bf16 v[80:83], v[174:177], v[182:185], 0
	v_mfma_f32_16x16x32_bf16 v[68:71], v[144:147], v[190:193], 0
	v_mfma_f32_16x16x32_bf16 v[64:67], v[174:177], v[190:193], 0
	v_mfma_f32_16x16x32_bf16 v[52:55], v[144:147], v[198:201], 0
	v_mfma_f32_16x16x32_bf16 v[48:51], v[174:177], v[198:201], 0
	v_mfma_f32_16x16x32_bf16 v[36:39], v[144:147], v[206:209], 0
	v_mfma_f32_16x16x32_bf16 v[32:35], v[174:177], v[206:209], 0
	v_mfma_f32_16x16x32_bf16 v[84:87], v[148:151], v[186:189], v[84:87]
	v_mfma_f32_16x16x32_bf16 v[80:83], v[178:181], v[186:189], v[80:83]
	v_mfma_f32_16x16x32_bf16 v[68:71], v[148:151], v[194:197], v[68:71]
	v_mfma_f32_16x16x32_bf16 v[64:67], v[178:181], v[194:197], v[64:67]
	v_mfma_f32_16x16x32_bf16 v[52:55], v[148:151], v[202:205], v[52:55]
	v_mfma_f32_16x16x32_bf16 v[48:51], v[178:181], v[202:205], v[48:51]
	v_mfma_f32_16x16x32_bf16 v[36:39], v[148:151], v[232:235], v[36:39]
	v_mfma_f32_16x16x32_bf16 v[32:35], v[178:181], v[232:235], v[32:35]
	s_setprio 0
	s_barrier
	s_add_i32 s69, 0, 0x18000
	s_add_i32 s70, 0, 0x1c000
	v_add_u32_e32 v140, s69, v227
	v_add_u32_e32 v152, s70, v227
	ds_read_b128 v[128:131], v140
	ds_read_b128 v[132:135], v140 offset:1024
	ds_read_b128 v[136:139], v140 offset:2048
	ds_read_b128 v[140:143], v140 offset:3072
	ds_read_b128 v[144:147], v152
	ds_read_b128 v[148:151], v152 offset:1024
	ds_read_b128 v[174:177], v152 offset:2048
	ds_read_b128 v[178:181], v152 offset:3072
	s_add_u32 s46, s46, s26
	s_addc_u32 s47, s47, 0
	s_mov_b32 m0, s8
	v_lshl_add_u64 v[246:247], s[46:47], 0, v[158:159]
	ds_read_b128 v[182:185], v230 offset:32768
	ds_read_b128 v[186:189], v230 offset:33792
	ds_read_b128 v[190:193], v230 offset:34816
	ds_read_b128 v[194:197], v230 offset:35840
	ds_read_b128 v[198:201], v230 offset:36864
	ds_read_b128 v[202:205], v230 offset:37888
	ds_read_b128 v[206:209], v230 offset:38912
	ds_read_b128 v[232:235], v230 offset:39936
	global_load_lds_dwordx4 v[246:247], off
	v_lshl_add_u64 v[246:247], s[46:47], 0, v[162:163]
	s_mov_b32 m0, s9
	s_nop 0
	global_load_lds_dwordx4 v[246:247], off
	s_waitcnt vmcnt(8)
	s_waitcnt lgkmcnt(0)
	s_barrier
	s_setprio 1
	s_waitcnt lgkmcnt(0)
	v_mfma_f32_16x16x32_bf16 v[16:19], v[128:131], v[182:185], v[16:19]
	v_mfma_f32_16x16x32_bf16 v[28:31], v[136:139], v[182:185], v[28:31]
	v_mfma_f32_16x16x32_bf16 v[12:15], v[128:131], v[190:193], v[12:15]
	v_mfma_f32_16x16x32_bf16 v[8:11], v[136:139], v[190:193], v[8:11]
	v_mfma_f32_16x16x32_bf16 v[124:127], v[128:131], v[198:201], v[124:127]
	v_mfma_f32_16x16x32_bf16 v[120:123], v[136:139], v[198:201], v[120:123]
	v_mfma_f32_16x16x32_bf16 v[108:111], v[128:131], v[206:209], v[108:111]
	v_mfma_f32_16x16x32_bf16 v[104:107], v[136:139], v[206:209], v[104:107]
	v_mfma_f32_16x16x32_bf16 v[16:19], v[132:135], v[186:189], v[16:19]
	v_mfma_f32_16x16x32_bf16 v[28:31], v[140:143], v[186:189], v[28:31]
	v_mfma_f32_16x16x32_bf16 v[12:15], v[132:135], v[194:197], v[12:15]
	v_mfma_f32_16x16x32_bf16 v[8:11], v[140:143], v[194:197], v[8:11]
	v_mfma_f32_16x16x32_bf16 v[124:127], v[132:135], v[202:205], v[124:127]
	v_mfma_f32_16x16x32_bf16 v[120:123], v[140:143], v[202:205], v[120:123]
	v_mfma_f32_16x16x32_bf16 v[108:111], v[132:135], v[232:235], v[108:111]
	v_mfma_f32_16x16x32_bf16 v[104:107], v[140:143], v[232:235], v[104:107]
	s_setprio 0
	s_setprio 1
	v_mfma_f32_16x16x32_bf16 v[24:27], v[144:147], v[182:185], v[24:27]
	v_mfma_f32_16x16x32_bf16 v[20:23], v[174:177], v[182:185], v[20:23]
	v_mfma_f32_16x16x32_bf16 v[4:7], v[144:147], v[190:193], v[4:7]
	v_mfma_f32_16x16x32_bf16 v[0:3], v[174:177], v[190:193], v[0:3]
	v_mfma_f32_16x16x32_bf16 v[116:119], v[144:147], v[198:201], v[116:119]
	v_mfma_f32_16x16x32_bf16 v[112:115], v[174:177], v[198:201], v[112:115]
	v_mfma_f32_16x16x32_bf16 v[100:103], v[144:147], v[206:209], v[100:103]
	v_mfma_f32_16x16x32_bf16 v[96:99], v[174:177], v[206:209], v[96:99]
	v_mfma_f32_16x16x32_bf16 v[24:27], v[148:151], v[186:189], v[24:27]
	v_mfma_f32_16x16x32_bf16 v[20:23], v[178:181], v[186:189], v[20:23]
	v_mfma_f32_16x16x32_bf16 v[4:7], v[148:151], v[194:197], v[4:7]
	v_mfma_f32_16x16x32_bf16 v[0:3], v[178:181], v[194:197], v[0:3]
	v_mfma_f32_16x16x32_bf16 v[116:119], v[148:151], v[202:205], v[116:119]
	v_mfma_f32_16x16x32_bf16 v[112:115], v[178:181], v[202:205], v[112:115]
	v_mfma_f32_16x16x32_bf16 v[100:103], v[148:151], v[232:235], v[100:103]
	v_mfma_f32_16x16x32_bf16 v[96:99], v[178:181], v[232:235], v[96:99]
	s_setprio 0
	s_barrier
	s_add_i32 s46, s69, s3
	v_lshl_add_u64 v[210:211], v[210:211], 0, s[6:7]
	s_mov_b32 m0, s46
	ds_read_b128 v[182:185], v230 offset:49152
	ds_read_b128 v[186:189], v230 offset:50176
	ds_read_b128 v[190:193], v230 offset:51200
	ds_read_b128 v[194:197], v230 offset:52224
	ds_read_b128 v[198:201], v230 offset:53248
	ds_read_b128 v[202:205], v230 offset:54272
	ds_read_b128 v[206:209], v230 offset:55296
	ds_read_b128 v[232:235], v230 offset:56320
	global_load_lds_dwordx4 v[210:211], off
	v_lshl_add_u64 v[210:211], v[236:237], 0, s[6:7]
	s_add_i32 m0, s46, 0x2000
	s_add_i32 s46, s70, s3
	global_load_lds_dwordx4 v[210:211], off
	v_lshl_add_u64 v[210:211], v[238:239], 0, s[6:7]
	s_mov_b32 m0, s46
	s_nop 0
	global_load_lds_dwordx4 v[210:211], off
	v_lshl_add_u64 v[210:211], v[240:241], 0, s[6:7]
	s_add_i32 m0, s46, 0x2000
	s_nop 0
	global_load_lds_dwordx4 v[210:211], off
	v_lshl_add_u64 v[210:211], v[242:243], 0, s[6:7]
	s_mov_b32 m0, s30
	s_nop 0
	global_load_lds_dwordx4 v[210:211], off
	v_lshl_add_u64 v[210:211], v[244:245], 0, s[6:7]
	s_mov_b32 m0, s31
	s_nop 0
	global_load_lds_dwordx4 v[210:211], off
	s_waitcnt vmcnt(8)
	s_waitcnt lgkmcnt(0)
	s_barrier
	s_setprio 1
	s_waitcnt lgkmcnt(0)
	v_mfma_f32_16x16x32_bf16 v[92:95], v[128:131], v[182:185], v[92:95]
	v_mfma_f32_16x16x32_bf16 v[88:91], v[136:139], v[182:185], v[88:91]
	v_mfma_f32_16x16x32_bf16 v[76:79], v[128:131], v[190:193], v[76:79]
	v_mfma_f32_16x16x32_bf16 v[72:75], v[136:139], v[190:193], v[72:75]
	v_mfma_f32_16x16x32_bf16 v[60:63], v[128:131], v[198:201], v[60:63]
	v_mfma_f32_16x16x32_bf16 v[56:59], v[136:139], v[198:201], v[56:59]
	v_mfma_f32_16x16x32_bf16 v[44:47], v[128:131], v[206:209], v[44:47]
	v_mfma_f32_16x16x32_bf16 v[40:43], v[136:139], v[206:209], v[40:43]
	v_mfma_f32_16x16x32_bf16 v[92:95], v[132:135], v[186:189], v[92:95]
	v_mfma_f32_16x16x32_bf16 v[88:91], v[140:143], v[186:189], v[88:91]
	v_mfma_f32_16x16x32_bf16 v[76:79], v[132:135], v[194:197], v[76:79]
	v_mfma_f32_16x16x32_bf16 v[72:75], v[140:143], v[194:197], v[72:75]
	v_mfma_f32_16x16x32_bf16 v[60:63], v[132:135], v[202:205], v[60:63]
	v_mfma_f32_16x16x32_bf16 v[56:59], v[140:143], v[202:205], v[56:59]
	v_mfma_f32_16x16x32_bf16 v[44:47], v[132:135], v[232:235], v[44:47]
	v_mfma_f32_16x16x32_bf16 v[40:43], v[140:143], v[232:235], v[40:43]
	s_setprio 0
	s_setprio 1
	v_mfma_f32_16x16x32_bf16 v[84:87], v[144:147], v[182:185], v[84:87]
	v_mfma_f32_16x16x32_bf16 v[80:83], v[174:177], v[182:185], v[80:83]
	v_mfma_f32_16x16x32_bf16 v[68:71], v[144:147], v[190:193], v[68:71]
	v_mfma_f32_16x16x32_bf16 v[64:67], v[174:177], v[190:193], v[64:67]
	v_mfma_f32_16x16x32_bf16 v[52:55], v[144:147], v[198:201], v[52:55]
	v_mfma_f32_16x16x32_bf16 v[48:51], v[174:177], v[198:201], v[48:51]
	v_mfma_f32_16x16x32_bf16 v[36:39], v[144:147], v[206:209], v[36:39]
	v_mfma_f32_16x16x32_bf16 v[32:35], v[174:177], v[206:209], v[32:35]
	v_mfma_f32_16x16x32_bf16 v[84:87], v[148:151], v[186:189], v[84:87]
	v_mfma_f32_16x16x32_bf16 v[80:83], v[178:181], v[186:189], v[80:83]
	v_mfma_f32_16x16x32_bf16 v[68:71], v[148:151], v[194:197], v[68:71]
	v_mfma_f32_16x16x32_bf16 v[64:67], v[178:181], v[194:197], v[64:67]
	v_mfma_f32_16x16x32_bf16 v[52:55], v[148:151], v[202:205], v[52:55]
	v_mfma_f32_16x16x32_bf16 v[48:51], v[178:181], v[202:205], v[48:51]
	v_mfma_f32_16x16x32_bf16 v[36:39], v[148:151], v[232:235], v[36:39]
	v_mfma_f32_16x16x32_bf16 v[32:35], v[178:181], v[232:235], v[32:35]
	s_setprio 0
	s_barrier
	s_add_u32 s44, s44, 0x100
	s_addc_u32 s45, s45, 0
	s_add_u32 s23, s23, 0x100
	s_addc_u32 s48, s48, 0
	s_cmp_ge_u32 s49, s88
	s_mov_b32 s46, s49
	s_cbranch_scc1 .LBB0_249
	s_nop 0
